# v_f1 + A-operand LDS-DMA pieces issued first in the heavy load segments of the P2/P7 K-loops
# speedup vs baseline: 1.0028x; 1.0021x over previous
.LBB0_659:
	ds_read_b128 v[80:83], v198
	ds_read_b128 v[84:87], v198 offset:1024
	ds_read_b128 v[104:107], v198 offset:2048
	ds_read_b128 v[108:111], v198 offset:3072
	ds_read_b128 v[128:131], v199
	ds_read_b128 v[132:135], v199 offset:1024
	ds_read_b128 v[152:155], v199 offset:2048
	ds_read_b128 v[156:159], v199 offset:3072
	s_add_u32 s10, s42, 0x100
	s_addc_u32 s11, s43, 0
	s_cmp_eq_u32 s86, 40
	s_cselect_b32 s50, s36, s10
	s_cselect_b32 s51, s37, s11
	s_cselect_b32 s48, s38, s84
	s_cselect_b32 s49, s39, s85
	s_add_u32 s40, s50, 0x80
	s_addc_u32 s41, s51, 0
	ds_read_b128 v[160:163], v200
	ds_read_b128 v[164:167], v200 offset:1024
	ds_read_b128 v[168:171], v200 offset:2048
	ds_read_b128 v[172:175], v200 offset:3072
	ds_read_b128 v[176:179], v200 offset:4096
	ds_read_b128 v[180:183], v200 offset:5120
	ds_read_b128 v[188:191], v200 offset:6144
	ds_read_b128 v[204:207], v200 offset:7168
	s_add_u32 s42, s42, 0xb0080
	s_addc_u32 s43, s43, 0
	s_mov_b32 s58, m0
	s_mov_b32 m0, s70
	s_nop 0
	global_load_lds_dwordx4 v194, s[42:43]
	s_mov_b32 m0, s58
	s_nop 0
	s_mov_b32 s58, m0
	s_mov_b32 m0, s73
	s_nop 0
	global_load_lds_dwordx4 v195, s[42:43]
	s_mov_b32 m0, s58
	s_waitcnt vmcnt(8)
	s_waitcnt lgkmcnt(0)
	s_barrier
	s_setprio 1
	s_waitcnt lgkmcnt(7)
	v_mfma_f32_16x16x32_bf16 v[136:139], v[80:83], v[160:163], v[136:139]
	v_mfma_f32_16x16x32_bf16 v[140:143], v[104:107], v[160:163], v[140:143]
	s_waitcnt lgkmcnt(5)
	v_mfma_f32_16x16x32_bf16 v[124:127], v[80:83], v[168:171], v[124:127]
	v_mfma_f32_16x16x32_bf16 v[120:123], v[104:107], v[168:171], v[120:123]
	s_waitcnt lgkmcnt(3)
	v_mfma_f32_16x16x32_bf16 v[100:103], v[80:83], v[176:179], v[100:103]
	v_mfma_f32_16x16x32_bf16 v[96:99], v[104:107], v[176:179], v[96:99]
	s_waitcnt lgkmcnt(1)
	v_mfma_f32_16x16x32_bf16 v[76:79], v[80:83], v[188:191], v[76:79]
	v_mfma_f32_16x16x32_bf16 v[72:75], v[104:107], v[188:191], v[72:75]
	v_mfma_f32_16x16x32_bf16 v[136:139], v[84:87], v[164:167], v[136:139]
	v_mfma_f32_16x16x32_bf16 v[140:143], v[108:111], v[164:167], v[140:143]
	v_mfma_f32_16x16x32_bf16 v[124:127], v[84:87], v[172:175], v[124:127]
	v_mfma_f32_16x16x32_bf16 v[120:123], v[108:111], v[172:175], v[120:123]
	v_mfma_f32_16x16x32_bf16 v[100:103], v[84:87], v[180:183], v[100:103]
	v_mfma_f32_16x16x32_bf16 v[96:99], v[108:111], v[180:183], v[96:99]
	s_waitcnt lgkmcnt(0)
	v_mfma_f32_16x16x32_bf16 v[76:79], v[84:87], v[204:207], v[76:79]
	v_mfma_f32_16x16x32_bf16 v[72:75], v[108:111], v[204:207], v[72:75]
	s_setprio 0
	s_setprio 1
	v_mfma_f32_16x16x32_bf16 v[148:151], v[128:131], v[160:163], v[148:151]
	v_mfma_f32_16x16x32_bf16 v[144:147], v[152:155], v[160:163], v[144:147]
	v_mfma_f32_16x16x32_bf16 v[116:119], v[128:131], v[168:171], v[116:119]
	v_mfma_f32_16x16x32_bf16 v[112:115], v[152:155], v[168:171], v[112:115]
	v_mfma_f32_16x16x32_bf16 v[92:95], v[128:131], v[176:179], v[92:95]
	v_mfma_f32_16x16x32_bf16 v[88:91], v[152:155], v[176:179], v[88:91]
	v_mfma_f32_16x16x32_bf16 v[68:71], v[128:131], v[188:191], v[68:71]
	v_mfma_f32_16x16x32_bf16 v[64:67], v[152:155], v[188:191], v[64:67]
	v_mfma_f32_16x16x32_bf16 v[148:151], v[132:135], v[164:167], v[148:151]
	v_mfma_f32_16x16x32_bf16 v[144:147], v[156:159], v[164:167], v[144:147]
	v_mfma_f32_16x16x32_bf16 v[116:119], v[132:135], v[172:175], v[116:119]
	v_mfma_f32_16x16x32_bf16 v[112:115], v[156:159], v[172:175], v[112:115]
	v_mfma_f32_16x16x32_bf16 v[92:95], v[132:135], v[180:183], v[92:95]
	v_mfma_f32_16x16x32_bf16 v[88:91], v[156:159], v[180:183], v[88:91]
	v_mfma_f32_16x16x32_bf16 v[68:71], v[132:135], v[204:207], v[68:71]
	v_mfma_f32_16x16x32_bf16 v[64:67], v[156:159], v[204:207], v[64:67]
	s_setprio 0
	s_barrier
	ds_read_b128 v[160:163], v200 offset:16384
	ds_read_b128 v[164:167], v200 offset:17408
	ds_read_b128 v[168:171], v200 offset:18432
	ds_read_b128 v[172:175], v200 offset:19456
	ds_read_b128 v[176:179], v200 offset:20480
	ds_read_b128 v[180:183], v200 offset:21504
	ds_read_b128 v[188:191], v200 offset:22528
	ds_read_b128 v[204:207], v200 offset:23552
	s_mov_b32 s32, m0
	s_mov_b32 m0, s4
	s_nop 0
	global_load_lds_dwordx4 v194, s[50:51]
	s_mov_b32 m0, s32
	s_nop 0
	s_mov_b32 s32, m0
	s_mov_b32 m0, s5
	s_nop 0
	global_load_lds_dwordx4 v195, s[50:51]
	s_mov_b32 m0, s32
	s_nop 0
	s_mov_b32 s42, m0
	s_mov_b32 m0, s71
	s_nop 0
	global_load_lds_dwordx4 v192, s[48:49]
	s_mov_b32 m0, s42
	s_nop 0
	s_mov_b32 s42, m0
	s_mov_b32 m0, s74
	s_nop 0
	global_load_lds_dwordx4 v193, s[48:49]
	s_mov_b32 m0, s42
	s_add_u32 s42, s48, 0xb0000
	s_addc_u32 s43, s49, 0
	s_mov_b32 s58, m0
	s_mov_b32 m0, s72
	s_nop 0
	global_load_lds_dwordx4 v192, s[42:43]
	s_mov_b32 m0, s58
	s_nop 0
	s_mov_b32 s58, m0
	s_mov_b32 m0, s75
	s_nop 0
	global_load_lds_dwordx4 v193, s[42:43]
	s_mov_b32 m0, s58
	s_waitcnt vmcnt(8)
	s_waitcnt lgkmcnt(0)
	s_barrier
	s_setprio 1
	s_waitcnt lgkmcnt(7)
	v_mfma_f32_16x16x32_bf16 v[60:63], v[80:83], v[160:163], v[60:63]
	v_mfma_f32_16x16x32_bf16 v[56:59], v[104:107], v[160:163], v[56:59]
	s_waitcnt lgkmcnt(5)
	v_mfma_f32_16x16x32_bf16 v[44:47], v[80:83], v[168:171], v[44:47]
	v_mfma_f32_16x16x32_bf16 v[40:43], v[104:107], v[168:171], v[40:43]
	s_waitcnt lgkmcnt(3)
	v_mfma_f32_16x16x32_bf16 v[28:31], v[80:83], v[176:179], v[28:31]
	v_mfma_f32_16x16x32_bf16 v[24:27], v[104:107], v[176:179], v[24:27]
	s_waitcnt lgkmcnt(1)
	v_mfma_f32_16x16x32_bf16 v[12:15], v[80:83], v[188:191], v[12:15]
	v_mfma_f32_16x16x32_bf16 v[8:11], v[104:107], v[188:191], v[8:11]
	v_mfma_f32_16x16x32_bf16 v[60:63], v[84:87], v[164:167], v[60:63]
	v_mfma_f32_16x16x32_bf16 v[56:59], v[108:111], v[164:167], v[56:59]
	v_mfma_f32_16x16x32_bf16 v[44:47], v[84:87], v[172:175], v[44:47]
	v_mfma_f32_16x16x32_bf16 v[40:43], v[108:111], v[172:175], v[40:43]
	v_mfma_f32_16x16x32_bf16 v[28:31], v[84:87], v[180:183], v[28:31]
	v_mfma_f32_16x16x32_bf16 v[24:27], v[108:111], v[180:183], v[24:27]
	s_waitcnt lgkmcnt(0)
	v_mfma_f32_16x16x32_bf16 v[12:15], v[84:87], v[204:207], v[12:15]
	v_mfma_f32_16x16x32_bf16 v[8:11], v[108:111], v[204:207], v[8:11]
	s_setprio 0
	s_setprio 1
	v_mfma_f32_16x16x32_bf16 v[52:55], v[128:131], v[160:163], v[52:55]
	v_mfma_f32_16x16x32_bf16 v[48:51], v[152:155], v[160:163], v[48:51]
	v_mfma_f32_16x16x32_bf16 v[36:39], v[128:131], v[168:171], v[36:39]
	v_mfma_f32_16x16x32_bf16 v[32:35], v[152:155], v[168:171], v[32:35]
	v_mfma_f32_16x16x32_bf16 v[20:23], v[128:131], v[176:179], v[20:23]
	v_mfma_f32_16x16x32_bf16 v[16:19], v[152:155], v[176:179], v[16:19]
	v_mfma_f32_16x16x32_bf16 v[4:7], v[128:131], v[188:191], v[4:7]
	v_mfma_f32_16x16x32_bf16 v[0:3], v[152:155], v[188:191], v[0:3]
	v_mfma_f32_16x16x32_bf16 v[52:55], v[132:135], v[164:167], v[52:55]
	v_mfma_f32_16x16x32_bf16 v[48:51], v[156:159], v[164:167], v[48:51]
	v_mfma_f32_16x16x32_bf16 v[36:39], v[132:135], v[172:175], v[36:39]
	v_mfma_f32_16x16x32_bf16 v[32:35], v[156:159], v[172:175], v[32:35]
	v_mfma_f32_16x16x32_bf16 v[20:23], v[132:135], v[180:183], v[20:23]
	v_mfma_f32_16x16x32_bf16 v[16:19], v[156:159], v[180:183], v[16:19]
	v_mfma_f32_16x16x32_bf16 v[4:7], v[132:135], v[204:207], v[4:7]
	v_mfma_f32_16x16x32_bf16 v[0:3], v[156:159], v[204:207], v[0:3]
	s_setprio 0
	s_barrier
	ds_read_b128 v[80:83], v201
	ds_read_b128 v[84:87], v201 offset:1024
	ds_read_b128 v[104:107], v201 offset:2048
	ds_read_b128 v[108:111], v201 offset:3072
	ds_read_b128 v[128:131], v202
	ds_read_b128 v[132:135], v202 offset:1024
	ds_read_b128 v[152:155], v202 offset:2048
	ds_read_b128 v[156:159], v202 offset:3072
	ds_read_b128 v[160:163], v200 offset:32768
	ds_read_b128 v[164:167], v200 offset:33792
	ds_read_b128 v[168:171], v200 offset:34816
	ds_read_b128 v[172:175], v200 offset:35840
	ds_read_b128 v[176:179], v200 offset:36864
	ds_read_b128 v[180:183], v200 offset:37888
	ds_read_b128 v[188:191], v200 offset:38912
	ds_read_b128 v[204:207], v200 offset:39936
	s_add_u32 s42, s50, 0xb0000
	s_addc_u32 s43, s51, 0
	s_mov_b32 s50, m0
	s_mov_b32 m0, s33
	s_nop 0
	global_load_lds_dwordx4 v194, s[42:43]
	s_mov_b32 m0, s50
	s_nop 0
	s_mov_b32 s50, m0
	s_mov_b32 m0, s52
	s_nop 0
	global_load_lds_dwordx4 v195, s[42:43]
	s_mov_b32 m0, s50
	s_waitcnt vmcnt(8)
	s_waitcnt lgkmcnt(0)
	s_barrier
	s_setprio 1
	s_waitcnt lgkmcnt(7)
	v_mfma_f32_16x16x32_bf16 v[136:139], v[80:83], v[160:163], v[136:139]
	v_mfma_f32_16x16x32_bf16 v[140:143], v[104:107], v[160:163], v[140:143]
	s_waitcnt lgkmcnt(5)
	v_mfma_f32_16x16x32_bf16 v[124:127], v[80:83], v[168:171], v[124:127]
	v_mfma_f32_16x16x32_bf16 v[120:123], v[104:107], v[168:171], v[120:123]
	s_waitcnt lgkmcnt(3)
	v_mfma_f32_16x16x32_bf16 v[100:103], v[80:83], v[176:179], v[100:103]
	v_mfma_f32_16x16x32_bf16 v[96:99], v[104:107], v[176:179], v[96:99]
	s_waitcnt lgkmcnt(1)
	v_mfma_f32_16x16x32_bf16 v[76:79], v[80:83], v[188:191], v[76:79]
	v_mfma_f32_16x16x32_bf16 v[72:75], v[104:107], v[188:191], v[72:75]
	v_mfma_f32_16x16x32_bf16 v[136:139], v[84:87], v[164:167], v[136:139]
	v_mfma_f32_16x16x32_bf16 v[140:143], v[108:111], v[164:167], v[140:143]
	v_mfma_f32_16x16x32_bf16 v[124:127], v[84:87], v[172:175], v[124:127]
	v_mfma_f32_16x16x32_bf16 v[120:123], v[108:111], v[172:175], v[120:123]
	v_mfma_f32_16x16x32_bf16 v[100:103], v[84:87], v[180:183], v[100:103]
	v_mfma_f32_16x16x32_bf16 v[96:99], v[108:111], v[180:183], v[96:99]
	s_waitcnt lgkmcnt(0)
	v_mfma_f32_16x16x32_bf16 v[76:79], v[84:87], v[204:207], v[76:79]
	v_mfma_f32_16x16x32_bf16 v[72:75], v[108:111], v[204:207], v[72:75]
	s_setprio 0
	s_setprio 1
	v_mfma_f32_16x16x32_bf16 v[148:151], v[128:131], v[160:163], v[148:151]
	v_mfma_f32_16x16x32_bf16 v[144:147], v[152:155], v[160:163], v[144:147]
	v_mfma_f32_16x16x32_bf16 v[116:119], v[128:131], v[168:171], v[116:119]
	v_mfma_f32_16x16x32_bf16 v[112:115], v[152:155], v[168:171], v[112:115]
	v_mfma_f32_16x16x32_bf16 v[92:95], v[128:131], v[176:179], v[92:95]
	v_mfma_f32_16x16x32_bf16 v[88:91], v[152:155], v[176:179], v[88:91]
	v_mfma_f32_16x16x32_bf16 v[68:71], v[128:131], v[188:191], v[68:71]
	v_mfma_f32_16x16x32_bf16 v[64:67], v[152:155], v[188:191], v[64:67]
	v_mfma_f32_16x16x32_bf16 v[148:151], v[132:135], v[164:167], v[148:151]
	v_mfma_f32_16x16x32_bf16 v[144:147], v[156:159], v[164:167], v[144:147]
	v_mfma_f32_16x16x32_bf16 v[116:119], v[132:135], v[172:175], v[116:119]
	v_mfma_f32_16x16x32_bf16 v[112:115], v[156:159], v[172:175], v[112:115]
	v_mfma_f32_16x16x32_bf16 v[92:95], v[132:135], v[180:183], v[92:95]
	v_mfma_f32_16x16x32_bf16 v[88:91], v[156:159], v[180:183], v[88:91]
	v_mfma_f32_16x16x32_bf16 v[68:71], v[132:135], v[204:207], v[68:71]
	v_mfma_f32_16x16x32_bf16 v[64:67], v[156:159], v[204:207], v[64:67]
	s_setprio 0
	s_barrier
	ds_read_b128 v[160:163], v200 offset:49152
	ds_read_b128 v[164:167], v200 offset:50176
	ds_read_b128 v[168:171], v200 offset:51200
	ds_read_b128 v[172:175], v200 offset:52224
	ds_read_b128 v[176:179], v200 offset:53248
	ds_read_b128 v[180:183], v200 offset:54272
	ds_read_b128 v[188:191], v200 offset:55296
	ds_read_b128 v[204:207], v200 offset:56320
	s_add_u32 s42, s48, 0x80
	s_addc_u32 s43, s49, 0
	s_mov_b32 s32, m0
	s_mov_b32 m0, s62
	s_nop 0
	global_load_lds_dwordx4 v194, s[40:41]
	s_mov_b32 m0, s32
	s_nop 0
	s_mov_b32 s32, m0
	s_mov_b32 m0, s63
	s_nop 0
	global_load_lds_dwordx4 v195, s[40:41]
	s_mov_b32 m0, s32
	s_nop 0
	s_mov_b32 s50, m0
	s_mov_b32 m0, s54
	s_nop 0
	global_load_lds_dwordx4 v192, s[42:43]
	s_mov_b32 m0, s50
	s_nop 0
	s_mov_b32 s50, m0
	s_mov_b32 m0, s55
	s_nop 0
	global_load_lds_dwordx4 v193, s[42:43]
	s_mov_b32 m0, s50
	s_add_u32 s42, s48, 0xb0080
	s_addc_u32 s43, s49, 0
	s_mov_b32 s48, m0
	s_mov_b32 m0, s68
	s_nop 0
	global_load_lds_dwordx4 v192, s[42:43]
	s_mov_b32 m0, s48
	s_nop 0
	s_mov_b32 s48, m0
	s_mov_b32 m0, s69
	s_nop 0
	global_load_lds_dwordx4 v193, s[42:43]
	s_mov_b32 m0, s48
	s_waitcnt vmcnt(8)
	s_waitcnt lgkmcnt(0)
	s_barrier
	s_setprio 1
	s_waitcnt lgkmcnt(7)
	v_mfma_f32_16x16x32_bf16 v[60:63], v[80:83], v[160:163], v[60:63]
	v_mfma_f32_16x16x32_bf16 v[56:59], v[104:107], v[160:163], v[56:59]
	s_waitcnt lgkmcnt(5)
	v_mfma_f32_16x16x32_bf16 v[44:47], v[80:83], v[168:171], v[44:47]
	v_mfma_f32_16x16x32_bf16 v[40:43], v[104:107], v[168:171], v[40:43]
	s_waitcnt lgkmcnt(3)
	v_mfma_f32_16x16x32_bf16 v[28:31], v[80:83], v[176:179], v[28:31]
	v_mfma_f32_16x16x32_bf16 v[24:27], v[104:107], v[176:179], v[24:27]
	s_waitcnt lgkmcnt(1)
	v_mfma_f32_16x16x32_bf16 v[12:15], v[80:83], v[188:191], v[12:15]
	v_mfma_f32_16x16x32_bf16 v[8:11], v[104:107], v[188:191], v[8:11]
	v_mfma_f32_16x16x32_bf16 v[60:63], v[84:87], v[164:167], v[60:63]
	v_mfma_f32_16x16x32_bf16 v[56:59], v[108:111], v[164:167], v[56:59]
	v_mfma_f32_16x16x32_bf16 v[44:47], v[84:87], v[172:175], v[44:47]
	v_mfma_f32_16x16x32_bf16 v[40:43], v[108:111], v[172:175], v[40:43]
	v_mfma_f32_16x16x32_bf16 v[28:31], v[84:87], v[180:183], v[28:31]
	v_mfma_f32_16x16x32_bf16 v[24:27], v[108:111], v[180:183], v[24:27]
	s_waitcnt lgkmcnt(0)
	v_mfma_f32_16x16x32_bf16 v[12:15], v[84:87], v[204:207], v[12:15]
	v_mfma_f32_16x16x32_bf16 v[8:11], v[108:111], v[204:207], v[8:11]
	s_setprio 0
	s_setprio 1
	v_mfma_f32_16x16x32_bf16 v[52:55], v[128:131], v[160:163], v[52:55]
	v_mfma_f32_16x16x32_bf16 v[48:51], v[152:155], v[160:163], v[48:51]
	v_mfma_f32_16x16x32_bf16 v[36:39], v[128:131], v[168:171], v[36:39]
	v_mfma_f32_16x16x32_bf16 v[32:35], v[152:155], v[168:171], v[32:35]
	v_mfma_f32_16x16x32_bf16 v[20:23], v[128:131], v[176:179], v[20:23]
	v_mfma_f32_16x16x32_bf16 v[16:19], v[152:155], v[176:179], v[16:19]
	v_mfma_f32_16x16x32_bf16 v[4:7], v[128:131], v[188:191], v[4:7]
	v_mfma_f32_16x16x32_bf16 v[0:3], v[152:155], v[188:191], v[0:3]
	v_mfma_f32_16x16x32_bf16 v[52:55], v[132:135], v[164:167], v[52:55]
	v_mfma_f32_16x16x32_bf16 v[48:51], v[156:159], v[164:167], v[48:51]
	v_mfma_f32_16x16x32_bf16 v[36:39], v[132:135], v[172:175], v[36:39]
	v_mfma_f32_16x16x32_bf16 v[32:35], v[156:159], v[172:175], v[32:35]
	v_mfma_f32_16x16x32_bf16 v[20:23], v[132:135], v[180:183], v[20:23]
	v_mfma_f32_16x16x32_bf16 v[16:19], v[156:159], v[180:183], v[16:19]
	v_mfma_f32_16x16x32_bf16 v[4:7], v[132:135], v[204:207], v[4:7]
	v_mfma_f32_16x16x32_bf16 v[0:3], v[156:159], v[204:207], v[0:3]
	s_setprio 0
	s_barrier
	s_add_i32 s86, s86, 2
	s_add_u32 s84, s84, 0x100
	s_addc_u32 s85, s85, 0
	s_cmp_gt_u32 s86, 41
	s_mov_b64 s[42:43], s[10:11]
	s_cbranch_scc0 .LBB0_659
	s_and_b64 vcc, exec, s[22:23]
	s_cbranch_vccz .LBB0_662
	s_barrier

.LBB0_1373:
	ds_read_b128 v[112:115], v174
	ds_read_b128 v[132:135], v174 offset:1024
	ds_read_b128 v[136:139], v174 offset:2048
	ds_read_b128 v[140:143], v174 offset:3072
	ds_read_b128 v[144:147], v175
	ds_read_b128 v[148:151], v175 offset:1024
	ds_read_b128 v[152:155], v175 offset:2048
	ds_read_b128 v[156:159], v175 offset:3072
	s_add_u32 s12, s16, 0x100
	s_addc_u32 s13, s17, 0
	s_cmp_eq_u32 s58, 40
	s_cselect_b32 s20, s8, s12
	s_cselect_b32 s21, s9, s13
	s_cselect_b32 s18, s10, s55
	s_cselect_b32 s19, s11, s57
	s_add_u32 s14, s20, 0x80
	s_addc_u32 s15, s21, 0
	ds_read_b128 v[160:163], v176
	ds_read_b128 v[180:183], v176 offset:1024
	ds_read_b128 v[184:187], v176 offset:2048
	ds_read_b128 v[188:191], v176 offset:3072
	ds_read_b128 v[192:195], v176 offset:4096
	ds_read_b128 v[196:199], v176 offset:5120
	ds_read_b128 v[200:203], v176 offset:6144
	ds_read_b128 v[204:207], v176 offset:7168
	s_add_u32 s16, s16, 0xb0080
	s_addc_u32 s17, s17, 0
	s_mov_b32 s59, m0
	s_mov_b32 m0, s34
	s_nop 0
	global_load_lds_dwordx4 v170, s[16:17]
	s_mov_b32 m0, s59
	s_nop 0
	s_mov_b32 s59, m0
	s_mov_b32 m0, s38
	s_nop 0
	global_load_lds_dwordx4 v171, s[16:17]
	s_mov_b32 m0, s59
	s_waitcnt vmcnt(8)
	s_waitcnt lgkmcnt(0)
	s_barrier
	s_setprio 1
	s_waitcnt lgkmcnt(7)
	v_mfma_f32_16x16x32_bf16 v[120:123], v[112:115], v[160:163], v[120:123]
	v_mfma_f32_16x16x32_bf16 v[116:119], v[136:139], v[160:163], v[116:119]
	s_waitcnt lgkmcnt(5)
	v_mfma_f32_16x16x32_bf16 v[108:111], v[112:115], v[184:187], v[108:111]
	v_mfma_f32_16x16x32_bf16 v[104:107], v[136:139], v[184:187], v[104:107]
	s_waitcnt lgkmcnt(3)
	v_mfma_f32_16x16x32_bf16 v[92:95], v[112:115], v[192:195], v[92:95]
	v_mfma_f32_16x16x32_bf16 v[88:91], v[136:139], v[192:195], v[88:91]
	s_waitcnt lgkmcnt(1)
	v_mfma_f32_16x16x32_bf16 v[76:79], v[112:115], v[200:203], v[76:79]
	v_mfma_f32_16x16x32_bf16 v[72:75], v[136:139], v[200:203], v[72:75]
	v_mfma_f32_16x16x32_bf16 v[120:123], v[132:135], v[180:183], v[120:123]
	v_mfma_f32_16x16x32_bf16 v[116:119], v[140:143], v[180:183], v[116:119]
	v_mfma_f32_16x16x32_bf16 v[108:111], v[132:135], v[188:191], v[108:111]
	v_mfma_f32_16x16x32_bf16 v[104:107], v[140:143], v[188:191], v[104:107]
	v_mfma_f32_16x16x32_bf16 v[92:95], v[132:135], v[196:199], v[92:95]
	v_mfma_f32_16x16x32_bf16 v[88:91], v[140:143], v[196:199], v[88:91]
	s_waitcnt lgkmcnt(0)
	v_mfma_f32_16x16x32_bf16 v[76:79], v[132:135], v[204:207], v[76:79]
	v_mfma_f32_16x16x32_bf16 v[72:75], v[140:143], v[204:207], v[72:75]
	s_setprio 0
	s_setprio 1
	v_mfma_f32_16x16x32_bf16 v[128:131], v[144:147], v[160:163], v[128:131]
	v_mfma_f32_16x16x32_bf16 v[124:127], v[152:155], v[160:163], v[124:127]
	v_mfma_f32_16x16x32_bf16 v[100:103], v[144:147], v[184:187], v[100:103]
	v_mfma_f32_16x16x32_bf16 v[96:99], v[152:155], v[184:187], v[96:99]
	v_mfma_f32_16x16x32_bf16 v[84:87], v[144:147], v[192:195], v[84:87]
	v_mfma_f32_16x16x32_bf16 v[80:83], v[152:155], v[192:195], v[80:83]
	v_mfma_f32_16x16x32_bf16 v[60:63], v[144:147], v[200:203], v[60:63]
	v_mfma_f32_16x16x32_bf16 v[56:59], v[152:155], v[200:203], v[56:59]
	v_mfma_f32_16x16x32_bf16 v[128:131], v[148:151], v[180:183], v[128:131]
	v_mfma_f32_16x16x32_bf16 v[124:127], v[156:159], v[180:183], v[124:127]
	v_mfma_f32_16x16x32_bf16 v[100:103], v[148:151], v[188:191], v[100:103]
	v_mfma_f32_16x16x32_bf16 v[96:99], v[156:159], v[188:191], v[96:99]
	v_mfma_f32_16x16x32_bf16 v[84:87], v[148:151], v[196:199], v[84:87]
	v_mfma_f32_16x16x32_bf16 v[80:83], v[156:159], v[196:199], v[80:83]
	v_mfma_f32_16x16x32_bf16 v[60:63], v[148:151], v[204:207], v[60:63]
	v_mfma_f32_16x16x32_bf16 v[56:59], v[156:159], v[204:207], v[56:59]
	s_setprio 0
	s_barrier
	ds_read_b128 v[160:163], v176 offset:16384
	ds_read_b128 v[180:183], v176 offset:17408
	ds_read_b128 v[184:187], v176 offset:18432
	ds_read_b128 v[188:191], v176 offset:19456
	ds_read_b128 v[192:195], v176 offset:20480
	ds_read_b128 v[196:199], v176 offset:21504
	ds_read_b128 v[200:203], v176 offset:22528
	ds_read_b128 v[204:207], v176 offset:23552
	s_mov_b32 s32, m0
	s_mov_b32 m0, s22
	s_nop 0
	global_load_lds_dwordx4 v170, s[20:21]
	s_mov_b32 m0, s32
	s_nop 0
	s_mov_b32 s32, m0
	s_mov_b32 m0, s23
	s_nop 0
	global_load_lds_dwordx4 v171, s[20:21]
	s_mov_b32 m0, s32
	s_nop 0
	s_mov_b32 s16, m0
	s_mov_b32 m0, s36
	s_nop 0
	global_load_lds_dwordx4 v168, s[18:19]
	s_mov_b32 m0, s16
	s_nop 0
	s_mov_b32 s16, m0
	s_mov_b32 m0, s39
	s_nop 0
	global_load_lds_dwordx4 v169, s[18:19]
	s_mov_b32 m0, s16
	s_add_u32 s16, s18, 0xb0000
	s_addc_u32 s17, s19, 0
	s_mov_b32 s59, m0
	s_mov_b32 m0, s37
	s_nop 0
	global_load_lds_dwordx4 v168, s[16:17]
	s_mov_b32 m0, s59
	s_nop 0
	s_mov_b32 s59, m0
	s_mov_b32 m0, s40
	s_nop 0
	global_load_lds_dwordx4 v169, s[16:17]
	s_mov_b32 m0, s59
	s_waitcnt vmcnt(8)
	s_waitcnt lgkmcnt(0)
	s_barrier
	s_setprio 1
	s_waitcnt lgkmcnt(7)
	v_mfma_f32_16x16x32_bf16 v[68:71], v[112:115], v[160:163], v[68:71]
	v_mfma_f32_16x16x32_bf16 v[64:67], v[136:139], v[160:163], v[64:67]
	s_waitcnt lgkmcnt(5)
	v_mfma_f32_16x16x32_bf16 v[44:47], v[112:115], v[184:187], v[44:47]
	v_mfma_f32_16x16x32_bf16 v[40:43], v[136:139], v[184:187], v[40:43]
	s_waitcnt lgkmcnt(3)
	v_mfma_f32_16x16x32_bf16 v[28:31], v[112:115], v[192:195], v[28:31]
	v_mfma_f32_16x16x32_bf16 v[24:27], v[136:139], v[192:195], v[24:27]
	s_waitcnt lgkmcnt(1)
	v_mfma_f32_16x16x32_bf16 v[12:15], v[112:115], v[200:203], v[12:15]
	v_mfma_f32_16x16x32_bf16 v[8:11], v[136:139], v[200:203], v[8:11]
	v_mfma_f32_16x16x32_bf16 v[68:71], v[132:135], v[180:183], v[68:71]
	v_mfma_f32_16x16x32_bf16 v[64:67], v[140:143], v[180:183], v[64:67]
	v_mfma_f32_16x16x32_bf16 v[44:47], v[132:135], v[188:191], v[44:47]
	v_mfma_f32_16x16x32_bf16 v[40:43], v[140:143], v[188:191], v[40:43]
	v_mfma_f32_16x16x32_bf16 v[28:31], v[132:135], v[196:199], v[28:31]
	v_mfma_f32_16x16x32_bf16 v[24:27], v[140:143], v[196:199], v[24:27]
	s_waitcnt lgkmcnt(0)
	v_mfma_f32_16x16x32_bf16 v[12:15], v[132:135], v[204:207], v[12:15]
	v_mfma_f32_16x16x32_bf16 v[8:11], v[140:143], v[204:207], v[8:11]
	s_setprio 0
	s_setprio 1
	v_mfma_f32_16x16x32_bf16 v[52:55], v[144:147], v[160:163], v[52:55]
	v_mfma_f32_16x16x32_bf16 v[48:51], v[152:155], v[160:163], v[48:51]
	v_mfma_f32_16x16x32_bf16 v[36:39], v[144:147], v[184:187], v[36:39]
	v_mfma_f32_16x16x32_bf16 v[32:35], v[152:155], v[184:187], v[32:35]
	v_mfma_f32_16x16x32_bf16 v[20:23], v[144:147], v[192:195], v[20:23]
	v_mfma_f32_16x16x32_bf16 v[16:19], v[152:155], v[192:195], v[16:19]
	v_mfma_f32_16x16x32_bf16 v[4:7], v[144:147], v[200:203], v[4:7]
	v_mfma_f32_16x16x32_bf16 v[0:3], v[152:155], v[200:203], v[0:3]
	v_mfma_f32_16x16x32_bf16 v[52:55], v[148:151], v[180:183], v[52:55]
	v_mfma_f32_16x16x32_bf16 v[48:51], v[156:159], v[180:183], v[48:51]
	v_mfma_f32_16x16x32_bf16 v[36:39], v[148:151], v[188:191], v[36:39]
	v_mfma_f32_16x16x32_bf16 v[32:35], v[156:159], v[188:191], v[32:35]
	v_mfma_f32_16x16x32_bf16 v[20:23], v[148:151], v[196:199], v[20:23]
	v_mfma_f32_16x16x32_bf16 v[16:19], v[156:159], v[196:199], v[16:19]
	v_mfma_f32_16x16x32_bf16 v[4:7], v[148:151], v[204:207], v[4:7]
	v_mfma_f32_16x16x32_bf16 v[0:3], v[156:159], v[204:207], v[0:3]
	s_setprio 0
	s_barrier
	ds_read_b128 v[112:115], v177
	ds_read_b128 v[132:135], v177 offset:1024
	ds_read_b128 v[136:139], v177 offset:2048
	ds_read_b128 v[140:143], v177 offset:3072
	ds_read_b128 v[144:147], v178
	ds_read_b128 v[148:151], v178 offset:1024
	ds_read_b128 v[152:155], v178 offset:2048
	ds_read_b128 v[156:159], v178 offset:3072
	ds_read_b128 v[160:163], v176 offset:32768
	ds_read_b128 v[180:183], v176 offset:33792
	ds_read_b128 v[184:187], v176 offset:34816
	ds_read_b128 v[188:191], v176 offset:35840
	ds_read_b128 v[192:195], v176 offset:36864
	ds_read_b128 v[196:199], v176 offset:37888
	ds_read_b128 v[200:203], v176 offset:38912
	ds_read_b128 v[204:207], v176 offset:39936
	s_add_u32 s16, s20, 0xb0000
	s_addc_u32 s17, s21, 0
	s_mov_b32 s20, m0
	s_mov_b32 m0, s24
	s_nop 0
	global_load_lds_dwordx4 v170, s[16:17]
	s_mov_b32 m0, s20
	s_nop 0
	s_mov_b32 s20, m0
	s_mov_b32 m0, s25
	s_nop 0
	global_load_lds_dwordx4 v171, s[16:17]
	s_mov_b32 m0, s20
	s_waitcnt vmcnt(8)
	s_waitcnt lgkmcnt(0)
	s_barrier
	s_setprio 1
	s_waitcnt lgkmcnt(7)
	v_mfma_f32_16x16x32_bf16 v[120:123], v[112:115], v[160:163], v[120:123]
	v_mfma_f32_16x16x32_bf16 v[116:119], v[136:139], v[160:163], v[116:119]
	s_waitcnt lgkmcnt(5)
	v_mfma_f32_16x16x32_bf16 v[108:111], v[112:115], v[184:187], v[108:111]
	v_mfma_f32_16x16x32_bf16 v[104:107], v[136:139], v[184:187], v[104:107]
	s_waitcnt lgkmcnt(3)
	v_mfma_f32_16x16x32_bf16 v[92:95], v[112:115], v[192:195], v[92:95]
	v_mfma_f32_16x16x32_bf16 v[88:91], v[136:139], v[192:195], v[88:91]
	s_waitcnt lgkmcnt(1)
	v_mfma_f32_16x16x32_bf16 v[76:79], v[112:115], v[200:203], v[76:79]
	v_mfma_f32_16x16x32_bf16 v[72:75], v[136:139], v[200:203], v[72:75]
	v_mfma_f32_16x16x32_bf16 v[120:123], v[132:135], v[180:183], v[120:123]
	v_mfma_f32_16x16x32_bf16 v[116:119], v[140:143], v[180:183], v[116:119]
	v_mfma_f32_16x16x32_bf16 v[108:111], v[132:135], v[188:191], v[108:111]
	v_mfma_f32_16x16x32_bf16 v[104:107], v[140:143], v[188:191], v[104:107]
	v_mfma_f32_16x16x32_bf16 v[92:95], v[132:135], v[196:199], v[92:95]
	v_mfma_f32_16x16x32_bf16 v[88:91], v[140:143], v[196:199], v[88:91]
	s_waitcnt lgkmcnt(0)
	v_mfma_f32_16x16x32_bf16 v[76:79], v[132:135], v[204:207], v[76:79]
	v_mfma_f32_16x16x32_bf16 v[72:75], v[140:143], v[204:207], v[72:75]
	s_setprio 0
	s_setprio 1
	v_mfma_f32_16x16x32_bf16 v[128:131], v[144:147], v[160:163], v[128:131]
	v_mfma_f32_16x16x32_bf16 v[124:127], v[152:155], v[160:163], v[124:127]
	v_mfma_f32_16x16x32_bf16 v[100:103], v[144:147], v[184:187], v[100:103]
	v_mfma_f32_16x16x32_bf16 v[96:99], v[152:155], v[184:187], v[96:99]
	v_mfma_f32_16x16x32_bf16 v[84:87], v[144:147], v[192:195], v[84:87]
	v_mfma_f32_16x16x32_bf16 v[80:83], v[152:155], v[192:195], v[80:83]
	v_mfma_f32_16x16x32_bf16 v[60:63], v[144:147], v[200:203], v[60:63]
	v_mfma_f32_16x16x32_bf16 v[56:59], v[152:155], v[200:203], v[56:59]
	v_mfma_f32_16x16x32_bf16 v[128:131], v[148:151], v[180:183], v[128:131]
	v_mfma_f32_16x16x32_bf16 v[124:127], v[156:159], v[180:183], v[124:127]
	v_mfma_f32_16x16x32_bf16 v[100:103], v[148:151], v[188:191], v[100:103]
	v_mfma_f32_16x16x32_bf16 v[96:99], v[156:159], v[188:191], v[96:99]
	v_mfma_f32_16x16x32_bf16 v[84:87], v[148:151], v[196:199], v[84:87]
	v_mfma_f32_16x16x32_bf16 v[80:83], v[156:159], v[196:199], v[80:83]
	v_mfma_f32_16x16x32_bf16 v[60:63], v[148:151], v[204:207], v[60:63]
	v_mfma_f32_16x16x32_bf16 v[56:59], v[156:159], v[204:207], v[56:59]
	s_setprio 0
	s_barrier
	ds_read_b128 v[160:163], v176 offset:49152
	ds_read_b128 v[180:183], v176 offset:50176
	ds_read_b128 v[184:187], v176 offset:51200
	ds_read_b128 v[188:191], v176 offset:52224
	ds_read_b128 v[192:195], v176 offset:53248
	ds_read_b128 v[196:199], v176 offset:54272
	ds_read_b128 v[200:203], v176 offset:55296
	ds_read_b128 v[204:207], v176 offset:56320
	s_add_u32 s16, s18, 0x80
	s_addc_u32 s17, s19, 0
	s_mov_b32 s32, m0
	s_mov_b32 m0, s29
	s_nop 0
	global_load_lds_dwordx4 v170, s[14:15]
	s_mov_b32 m0, s32
	s_nop 0
	s_mov_b32 s32, m0
	s_mov_b32 m0, s30
	s_nop 0
	global_load_lds_dwordx4 v171, s[14:15]
	s_mov_b32 m0, s32
	s_nop 0
	s_mov_b32 s20, m0
	s_mov_b32 m0, s27
	s_nop 0
	global_load_lds_dwordx4 v168, s[16:17]
	s_mov_b32 m0, s20
	s_nop 0
	s_mov_b32 s20, m0
	s_mov_b32 m0, s28
	s_nop 0
	global_load_lds_dwordx4 v169, s[16:17]
	s_mov_b32 m0, s20
	s_add_u32 s16, s18, 0xb0080
	s_addc_u32 s17, s19, 0
	s_mov_b32 s18, m0
	s_mov_b32 m0, s31
	s_nop 0
	global_load_lds_dwordx4 v168, s[16:17]
	s_mov_b32 m0, s18
	s_nop 0
	s_mov_b32 s18, m0
	s_mov_b32 m0, s33
	s_nop 0
	global_load_lds_dwordx4 v169, s[16:17]
	s_mov_b32 m0, s18
	s_waitcnt vmcnt(8)
	s_waitcnt lgkmcnt(0)
	s_barrier
	s_setprio 1
	s_waitcnt lgkmcnt(7)
	v_mfma_f32_16x16x32_bf16 v[68:71], v[112:115], v[160:163], v[68:71]
	v_mfma_f32_16x16x32_bf16 v[64:67], v[136:139], v[160:163], v[64:67]
	s_waitcnt lgkmcnt(5)
	v_mfma_f32_16x16x32_bf16 v[44:47], v[112:115], v[184:187], v[44:47]
	v_mfma_f32_16x16x32_bf16 v[40:43], v[136:139], v[184:187], v[40:43]
	s_waitcnt lgkmcnt(3)
	v_mfma_f32_16x16x32_bf16 v[28:31], v[112:115], v[192:195], v[28:31]
	v_mfma_f32_16x16x32_bf16 v[24:27], v[136:139], v[192:195], v[24:27]
	s_waitcnt lgkmcnt(1)
	v_mfma_f32_16x16x32_bf16 v[12:15], v[112:115], v[200:203], v[12:15]
	v_mfma_f32_16x16x32_bf16 v[8:11], v[136:139], v[200:203], v[8:11]
	v_mfma_f32_16x16x32_bf16 v[68:71], v[132:135], v[180:183], v[68:71]
	v_mfma_f32_16x16x32_bf16 v[64:67], v[140:143], v[180:183], v[64:67]
	v_mfma_f32_16x16x32_bf16 v[44:47], v[132:135], v[188:191], v[44:47]
	v_mfma_f32_16x16x32_bf16 v[40:43], v[140:143], v[188:191], v[40:43]
	v_mfma_f32_16x16x32_bf16 v[28:31], v[132:135], v[196:199], v[28:31]
	v_mfma_f32_16x16x32_bf16 v[24:27], v[140:143], v[196:199], v[24:27]
	s_waitcnt lgkmcnt(0)
	v_mfma_f32_16x16x32_bf16 v[12:15], v[132:135], v[204:207], v[12:15]
	v_mfma_f32_16x16x32_bf16 v[8:11], v[140:143], v[204:207], v[8:11]
	s_setprio 0
	s_setprio 1
	v_mfma_f32_16x16x32_bf16 v[52:55], v[144:147], v[160:163], v[52:55]
	v_mfma_f32_16x16x32_bf16 v[48:51], v[152:155], v[160:163], v[48:51]
	v_mfma_f32_16x16x32_bf16 v[36:39], v[144:147], v[184:187], v[36:39]
	v_mfma_f32_16x16x32_bf16 v[32:35], v[152:155], v[184:187], v[32:35]
	v_mfma_f32_16x16x32_bf16 v[20:23], v[144:147], v[192:195], v[20:23]
	v_mfma_f32_16x16x32_bf16 v[16:19], v[152:155], v[192:195], v[16:19]
	v_mfma_f32_16x16x32_bf16 v[4:7], v[144:147], v[200:203], v[4:7]
	v_mfma_f32_16x16x32_bf16 v[0:3], v[152:155], v[200:203], v[0:3]
	v_mfma_f32_16x16x32_bf16 v[52:55], v[148:151], v[180:183], v[52:55]
	v_mfma_f32_16x16x32_bf16 v[48:51], v[156:159], v[180:183], v[48:51]
	v_mfma_f32_16x16x32_bf16 v[36:39], v[148:151], v[188:191], v[36:39]
	v_mfma_f32_16x16x32_bf16 v[32:35], v[156:159], v[188:191], v[32:35]
	v_mfma_f32_16x16x32_bf16 v[20:23], v[148:151], v[196:199], v[20:23]
	v_mfma_f32_16x16x32_bf16 v[16:19], v[156:159], v[196:199], v[16:19]
	v_mfma_f32_16x16x32_bf16 v[4:7], v[148:151], v[204:207], v[4:7]
	v_mfma_f32_16x16x32_bf16 v[0:3], v[156:159], v[204:207], v[0:3]
	s_setprio 0
	s_barrier
	s_add_i32 s58, s58, 2
	s_add_u32 s55, s55, 0x100
	s_addc_u32 s57, s57, 0
	s_cmp_gt_u32 s58, 41
	s_mov_b64 s[16:17], s[12:13]
	s_cbranch_scc0 .LBB0_1373
	s_and_b64 vcc, exec, s[6:7]
	s_cbranch_vccz .LBB0_1376
	s_barrier
